# per-WG L2 writeback after GU-shadow weight conversion; post-down barrier L0-2 skips buffer_wbl2 in local mode
# speedup vs baseline: 1.0046x; 1.0046x over previous
.LBB0_1164:
	s_waitcnt vmcnt(0)
	s_barrier
	v_readfirstlane_b32 s2, v193
	s_nop 3
	s_lshr_b32 s2, s2, 6
	s_cmp_lg_u32 s2, 0
	s_cbranch_scc1 .Lcf_skipa
	s_mov_b64 s[2:3], exec
	s_mov_b64 exec, 1
	buffer_wbl2 sc1
	s_mov_b64 exec, s[2:3]
	s_waitcnt vmcnt(0)
